# s5 pass C item start: group parameter loads and their kernarg pointer loads issued together with the u-row loads (one exposed latency instead of two plus three scalar round trips)
# speedup vs baseline: 1.0037x; 1.0037x over previous
.LBB0_859:
	s_load_dwordx2 s[4:5], s[0:1], 0x150
	s_load_dwordx2 s[6:7], s[0:1], 0xa8
	s_load_dwordx2 s[8:9], s[0:1], 0x98
	s_load_dwordx2 s[10:11], s[0:1], 0xa0
	v_and_b32_e32 v51, 0x7f, v33
	v_ashrrev_i32_e32 v16, 7, v33
	v_mul_u32_u24_e32 v0, 0x68000, v51
	v_lshlrev_b32_e32 v168, 2, v0
	v_lshlrev_b32_e32 v90, 4, v16
	s_waitcnt lgkmcnt(0)
	v_lshl_add_u64 v[0:1], s[4:5], 0, v[168:169]
	v_ashrrev_i32_e32 v91, 31, v90
	v_lshl_add_u64 v[0:1], v[90:91], 2, v[0:1]
	v_mov_b32_e32 v39, v169
	v_lshl_add_u64 v[8:9], v[0:1], 0, v[38:39]
	s_mov_b64 s[4:5], 0xd645f20
	s_mov_b32 s2, 0xd645000
	v_lshl_add_u64 v[12:13], v[8:9], 0, s[4:5]
	v_add_co_u32_e32 v8, vcc, s2, v8
	global_load_dwordx4 v[0:3], v[12:13], off offset:32
	global_load_dwordx4 v[4:7], v[12:13], off offset:16
	v_addc_co_u32_e32 v9, vcc, 0, v9, vcc
	global_load_dwordx4 v[8:11], v[8:9], off offset:3872
	s_nop 0
	global_load_dwordx4 v[12:15], v[12:13], off offset:48
	v_readlane_b32 s2, v255, 26
	v_add_u32_e32 v232, s2, v16
	v_ashrrev_i32_e32 v233, 31, v232
	v_lshl_add_u64 v[234:235], v[232:233], 2, s[6:7]
	global_load_dword v242, v[234:235], off
	v_lshl_or_b32 v240, v232, 6, v35
	v_ashrrev_i32_e32 v241, 31, v240
	v_lshlrev_b64 v[240:241], 2, v[240:241]
	v_lshl_add_u64 v[244:245], s[8:9], 0, v[240:241]
	global_load_dword v54, v[244:245], off
	v_lshl_add_u64 v[246:247], s[10:11], 0, v[240:241]
	global_load_dword v55, v[246:247], off
	s_waitcnt vmcnt(3)
	ds_write_b128 v111, v[4:7] offset:16
	ds_write_b128 v111, v[0:3] offset:32
	ds_write_b128 v111, v[8:11]
	ds_write_b128 v111, v[12:15] offset:48
	s_waitcnt lgkmcnt(0)
	v_add_u32_e32 v0, s2, v16
	v_ashrrev_i32_e32 v1, 31, v0
	s_brev_b32 s2, 18
	s_mov_b32 s4, 0x6dc9c883
	s_mov_b32 s5, 0x3fc45f30
	s_waitcnt vmcnt(0)
	v_mov_b32_e32 v6, v242
	v_mul_f32_e32 v2, 0x3fb8aa3b, v6
	v_exp_f32_e32 v41, v2
	s_nop 0
	v_mul_f32_e32 v2, v41, v55
	v_cvt_f64_f32_e32 v[2:3], v2
	v_mul_f64 v[4:5], v[2:3], s[4:5]
	s_mov_b32 s4, 0x54442d18
	v_rndne_f64_e32 v[4:5], v[4:5]
	s_mov_b32 s5, 0xc01921fb
	v_fmac_f64_e32 v[2:3], s[4:5], v[4:5]
	v_cvt_f32_f64_e32 v39, v[2:3]
	v_and_b32_e32 v2, 0x7fffffff, v39
	v_lshrrev_b32_e32 v3, 23, v2
	v_and_b32_e32 v4, 0x7fffff, v2
	v_cmp_nlt_f32_e64 s[4:5], |v39|, s2
	v_add_u32_e32 v5, 0xffffff88, v3
	v_or_b32_e32 v3, 0x800000, v4
	s_and_saveexec_b64 s[6:7], s[4:5]
	s_xor_b64 s[24:25], exec, s[6:7]
	s_cbranch_execz .LBB0_861
	v_cmp_lt_u32_e32 vcc, 63, v5
	v_not_b32_e32 v4, 63
	s_mov_b32 s2, 0xfe5163ab
	v_cndmask_b32_e32 v4, 0, v4, vcc
	v_add_u32_e32 v4, v4, v5
	v_cmp_lt_u32_e64 s[6:7], 31, v4
	s_nop 1
	v_cndmask_b32_e64 v6, 0, v236, s[6:7]
	v_add_u32_e32 v4, v6, v4
	v_cmp_lt_u32_e64 s[8:9], 31, v4
	s_nop 1
	v_cndmask_b32_e64 v6, 0, v236, s[8:9]
	v_add_u32_e32 v4, v6, v4
	v_mad_u64_u32 v[6:7], s[10:11], v3, s2, 0
	v_mov_b32_e32 v168, v7
	s_mov_b32 s2, 0x3c439041
	v_mad_u64_u32 v[8:9], s[10:11], v3, s2, v[168:169]
	v_mov_b32_e32 v168, v9
	s_mov_b32 s2, 0xdb629599
	v_mad_u64_u32 v[10:11], s[10:11], v3, s2, v[168:169]
	v_mov_b32_e32 v168, v11
	s_mov_b32 s2, 0xf534ddc0
	v_mad_u64_u32 v[12:13], s[10:11], v3, s2, v[168:169]
	v_mov_b32_e32 v168, v13
	s_mov_b32 s2, 0xfc2757d1
	v_mad_u64_u32 v[14:15], s[10:11], v3, s2, v[168:169]
	v_mov_b32_e32 v168, v15
	s_mov_b32 s2, 0x4e441529
	v_mad_u64_u32 v[16:17], s[10:11], v3, s2, v[168:169]
	v_mov_b32_e32 v168, v17
	s_mov_b32 s2, 0xa2f9836e
	v_mad_u64_u32 v[18:19], s[10:11], v3, s2, v[168:169]
	v_cndmask_b32_e32 v7, v16, v12, vcc
	v_cndmask_b32_e32 v9, v18, v14, vcc
	v_cndmask_b32_e32 v13, v19, v16, vcc
	v_cndmask_b32_e64 v11, v9, v7, s[6:7]
	v_cndmask_b32_e64 v9, v13, v9, s[6:7]
	v_cndmask_b32_e32 v13, v14, v10, vcc
	v_cndmask_b32_e64 v7, v7, v13, s[6:7]
	v_cndmask_b32_e64 v9, v9, v11, s[8:9]
	v_cndmask_b32_e64 v11, v11, v7, s[8:9]
	v_sub_u32_e32 v14, 32, v4
	v_alignbit_b32 v15, v9, v11, v14
	v_cmp_eq_u32_e64 s[10:11], 0, v4
	v_cndmask_b32_e32 v8, v12, v8, vcc
	v_cndmask_b32_e32 v6, v10, v6, vcc
	v_cndmask_b32_e64 v4, v15, v9, s[10:11]
	v_cndmask_b32_e64 v9, v13, v8, s[6:7]
	v_cndmask_b32_e64 v7, v7, v9, s[8:9]
	v_alignbit_b32 v12, v11, v7, v14
	v_cndmask_b32_e64 v11, v12, v11, s[10:11]
	v_bfe_u32 v15, v4, 29, 1
	v_cndmask_b32_e64 v6, v8, v6, s[6:7]
	v_alignbit_b32 v12, v4, v11, 30
	v_sub_u32_e32 v16, 0, v15
	v_cndmask_b32_e64 v6, v9, v6, s[8:9]
	v_xor_b32_e32 v12, v12, v16
	v_alignbit_b32 v8, v7, v6, v14
	v_cndmask_b32_e64 v7, v8, v7, s[10:11]
	v_ffbh_u32_e32 v9, v12
	v_alignbit_b32 v8, v11, v7, 30
	v_min_u32_e32 v9, 32, v9
	v_alignbit_b32 v6, v7, v6, 30
	v_xor_b32_e32 v8, v8, v16
	v_sub_u32_e32 v10, 31, v9
	v_xor_b32_e32 v6, v6, v16
	v_alignbit_b32 v11, v12, v8, v10
	v_alignbit_b32 v6, v8, v6, v10
	v_alignbit_b32 v7, v11, v6, 9
	v_ffbh_u32_e32 v8, v7
	v_min_u32_e32 v8, 32, v8
	v_lshrrev_b32_e32 v13, 29, v4
	v_not_b32_e32 v10, v8
	v_alignbit_b32 v6, v7, v6, v10
	v_lshlrev_b32_e32 v7, 31, v13
	v_or_b32_e32 v10, 0x33000000, v7
	v_add_lshl_u32 v8, v8, v9, 23
	v_lshrrev_b32_e32 v6, 9, v6
	v_sub_u32_e32 v8, v10, v8
	v_or_b32_e32 v7, 0.5, v7
	v_lshlrev_b32_e32 v9, 23, v9
	v_or_b32_e32 v6, v8, v6
	v_lshrrev_b32_e32 v8, 9, v11
	v_sub_u32_e32 v7, v7, v9
	v_or_b32_e32 v7, v8, v7
	v_mul_f32_e32 v8, 0x3fc90fda, v7
	s_mov_b32 s2, 0x3fc90fda
	v_fma_f32 v9, v7, s2, -v8
	v_fmac_f32_e32 v9, 0x33a22168, v7
	v_fmac_f32_e32 v9, 0x3fc90fda, v6
	v_lshrrev_b32_e32 v4, 30, v4
	v_add_f32_e32 v53, v8, v9
	v_add_u32_e32 v4, v15, v4
